# speedup vs baseline: 1.0110x; 1.0110x over previous
; __global__ void __launch_bounds__(512, 2) fwd_megakernel(Args a) {
;     ...
;                 for (int i = 0; i < NCH; ++i) { P3_CONS(i); __syncthreads(); }
.LBB0_308:
	s_bitcmp1_b32 s14, 0
	s_cselect_b32 s2, 0xc000, 0
	s_add_i32 s2, s2, 0
	v_lshl_add_u32 v40, v164, 2, s2
	s_add_i32 s2, s2, s15
	v_lshl_add_u32 v52, v128, 2, s2
	ds_read_b128 v[8:11], v40 offset:256
	ds_read_b128 v[16:19], v40 offset:768
	ds_read2st64_b32 v[24:25], v52 offset0:5 offset1:11
	ds_read_b128 v[4:7], v40 offset:0
	ds_read_b128 v[20:23], v40 offset:1024
	ds_read_b128 v[12:15], v40 offset:512
	ds_read_b128 v[64:67], v40 offset:1792
	ds_read_b128 v[72:75], v40 offset:2304
	ds_read_b128 v[60:63], v40 offset:1536
	ds_read_b128 v[76:79], v40 offset:2560
	ds_read_b128 v[68:71], v40 offset:2048
	ds_read_b128 v[86:89], v40 offset:3328
	ds_read_b128 v[94:97], v40 offset:3840
	ds_read2st64_b32 v[102:103], v52 offset0:17 offset1:23
	ds_read_b128 v[82:85], v40 offset:3072
	ds_read_b128 v[98:101], v40 offset:4096
	ds_read_b128 v[90:93], v40 offset:3584
	v_add_f32_dpp v185, v46, v46 row_mirror row_mask:0xf bank_mask:0x3
	v_add_f32_dpp v186, v47, v47 row_mirror row_mask:0xf bank_mask:0x3
	v_add_f32_dpp v187, v48, v48 row_mirror row_mask:0xf bank_mask:0x3
	v_add_f32_dpp v185, v55, v55 row_mirror row_mask:0xf bank_mask:0xc
	v_add_f32_dpp v186, v56, v56 row_mirror row_mask:0xf bank_mask:0xc
	v_add_f32_dpp v187, v57, v57 row_mirror row_mask:0xf bank_mask:0xc
	v_add_f32_dpp v188, v49, v49 row_mirror row_mask:0xf bank_mask:0x3
	v_add_f32_dpp v189, v50, v50 row_mirror row_mask:0xf bank_mask:0x3
	v_add_f32_dpp v190, v51, v51 row_mirror row_mask:0xf bank_mask:0x3
	v_add_f32_dpp v188, v58, v58 row_mirror row_mask:0xf bank_mask:0xc
	v_add_f32_dpp v189, v59, v59 row_mirror row_mask:0xf bank_mask:0xc
	v_add_f32_dpp v190, v126, v126 row_mirror row_mask:0xf bank_mask:0xc
	v_add_f32_dpp v191, v53, v53 row_mirror row_mask:0xf bank_mask:0x3
	v_add_f32_dpp v192, v54, v54 row_mirror row_mask:0xf bank_mask:0x3
	v_add_f32_dpp v141, v185, v185 row_half_mirror row_mask:0xf bank_mask:0x5
	v_add_f32_dpp v191, v127, v127 row_mirror row_mask:0xf bank_mask:0xc
	v_add_f32_dpp v192, v139, v139 row_mirror row_mask:0xf bank_mask:0xc
	v_add_f32_dpp v141, v189, v189 row_half_mirror row_mask:0xf bank_mask:0xa
	v_add_f32_dpp v142, v186, v186 row_half_mirror row_mask:0xf bank_mask:0x5
	v_add_f32_dpp v143, v187, v187 row_half_mirror row_mask:0xf bank_mask:0x5
	v_add_f32_dpp v144, v188, v188 row_half_mirror row_mask:0xf bank_mask:0x5
	v_add_f32_dpp v142, v190, v190 row_half_mirror row_mask:0xf bank_mask:0xa
	v_add_f32_dpp v143, v191, v191 row_half_mirror row_mask:0xf bank_mask:0xa
	v_add_f32_dpp v144, v192, v192 row_half_mirror row_mask:0xf bank_mask:0xa
	s_waitcnt lgkmcnt(6)
	v_pk_mul_f32 v[26:27], v[0:1], v[8:9]
	v_pk_mul_f32 v[30:31], v[16:17], v[24:25] op_sel_hi:[1,0]
	v_pk_mul_f32 v[32:33], v[18:19], v[24:25] op_sel_hi:[1,0]
	v_pk_fma_f32 v[26:27], v[2:3], v[10:11], v[26:27]
	v_cndmask_b32_e64 v145, v143, v141, s[8:9]
	v_pk_fma_f32 v[34:35], v[0:1], v[4:5], v[30:31]
	v_add_f32_e32 v28, v26, v27
	v_pk_fma_f32 v[36:37], v[2:3], v[6:7], v[32:33]
	v_cndmask_b32_e64 v155, v141, v143, s[8:9]
	v_add_f32_dpp v28, v28, v28 row_ror:8 row_mask:0xf bank_mask:0xf bound_ctrl:1
	ds_read_b128 v[108:111], v40 offset:4864
	ds_read_b128 v[116:119], v40 offset:5376
	v_add_f32_dpp v28, v28, v28 row_ror:4 row_mask:0xf bank_mask:0xf bound_ctrl:1
	v_add_f32_dpp v145, v155, v145 quad_perm:[2,3,0,1] row_mask:0xf bank_mask:0xf bound_ctrl:1
	ds_read_b128 v[104:107], v40 offset:4608
	v_add_f32_dpp v28, v28, v28 row_ror:2 row_mask:0xf bank_mask:0xf bound_ctrl:1
	ds_read_b128 v[120:123], v40 offset:5632
	ds_read_b128 v[112:115], v40 offset:5120
	v_add_f32_dpp v28, v28, v28 row_ror:1 row_mask:0xf bank_mask:0xf bound_ctrl:1
	v_cndmask_b32_e64 v146, v144, v142, s[8:9]
	v_cndmask_b32_e64 v157, v142, v144, s[8:9]
	v_pk_fma_f32 v[0:1], v[12:13], v[28:29], v[34:35] op_sel_hi:[1,0,1]
	v_pk_fma_f32 v[2:3], v[14:15], v[28:29], v[36:37] op_sel_hi:[1,0,1]
	v_add_f32_dpp v146, v157, v146 quad_perm:[2,3,0,1] row_mask:0xf bank_mask:0xf bound_ctrl:1
	v_pk_mul_f32 v[26:27], v[0:1], v[64:65]
	v_pk_mul_f32 v[30:31], v[72:73], v[24:25] op_sel:[0,1] op_sel_hi:[1,1]
	v_pk_mul_f32 v[32:33], v[74:75], v[24:25] op_sel:[0,1] op_sel_hi:[1,1]
	v_pk_fma_f32 v[26:27], v[2:3], v[66:67], v[26:27]
	v_pk_mul_f32 v[38:39], v[0:1], v[20:21]
	v_pk_fma_f32 v[34:35], v[0:1], v[60:61], v[30:31]
	v_add_f32_e32 v28, v26, v27
	v_pk_fma_f32 v[36:37], v[2:3], v[62:63], v[32:33]
	v_pk_fma_f32 v[38:39], v[2:3], v[22:23], v[38:39]
	v_add_f32_dpp v28, v28, v28 row_ror:8 row_mask:0xf bank_mask:0xf bound_ctrl:1
	ds_read_b128 v[8:11], v40 offset:6400
	ds_read_b128 v[16:19], v40 offset:6912
	v_add_f32_dpp v28, v28, v28 row_ror:4 row_mask:0xf bank_mask:0xf bound_ctrl:1
	v_add_f32_e32 v169, v38, v39
	ds_read2st64_b32 v[24:25], v52 offset0:29 offset1:35
	v_add_f32_dpp v28, v28, v28 row_ror:2 row_mask:0xf bank_mask:0xf bound_ctrl:1
	ds_read_b128 v[4:7], v40 offset:6144
	ds_read_b128 v[20:23], v40 offset:7168
	v_add_f32_dpp v28, v28, v28 row_ror:1 row_mask:0xf bank_mask:0xf bound_ctrl:1
	ds_read_b128 v[12:15], v40 offset:6656
	v_cndmask_b32_e64 v147, v146, v145, s[10:11]
	v_pk_fma_f32 v[0:1], v[68:69], v[28:29], v[34:35] op_sel_hi:[1,0,1]
	v_pk_fma_f32 v[2:3], v[70:71], v[28:29], v[36:37] op_sel_hi:[1,0,1]
	v_cndmask_b32_e64 v159, v145, v146, s[10:11]
	s_waitcnt lgkmcnt(6)
	v_pk_mul_f32 v[26:27], v[0:1], v[86:87]
	v_pk_mul_f32 v[30:31], v[94:95], v[102:103] op_sel_hi:[1,0]
	v_pk_mul_f32 v[32:33], v[96:97], v[102:103] op_sel_hi:[1,0]
	v_pk_fma_f32 v[26:27], v[2:3], v[88:89], v[26:27]
	v_pk_mul_f32 v[38:39], v[0:1], v[76:77]
	v_pk_fma_f32 v[34:35], v[0:1], v[82:83], v[30:31]
	v_add_f32_e32 v28, v26, v27
	v_pk_fma_f32 v[36:37], v[2:3], v[84:85], v[32:33]
	v_pk_fma_f32 v[38:39], v[2:3], v[78:79], v[38:39]
	v_add_f32_dpp v28, v28, v28 row_ror:8 row_mask:0xf bank_mask:0xf bound_ctrl:1
	ds_read_b128 v[64:67], v40 offset:7936
	ds_read_b128 v[72:75], v40 offset:8448
	v_add_f32_dpp v28, v28, v28 row_ror:4 row_mask:0xf bank_mask:0xf bound_ctrl:1
	v_add_f32_e32 v170, v38, v39
	ds_read_b128 v[60:63], v40 offset:7680
	v_add_f32_dpp v28, v28, v28 row_ror:2 row_mask:0xf bank_mask:0xf bound_ctrl:1
	ds_read_b128 v[76:79], v40 offset:8704
	ds_read_b128 v[68:71], v40 offset:8192
	v_add_f32_dpp v28, v28, v28 row_ror:1 row_mask:0xf bank_mask:0xf bound_ctrl:1
	v_add_f32_dpp v147, v159, v147 quad_perm:[1,0,3,2] row_mask:0xf bank_mask:0xf bound_ctrl:1
	v_pk_fma_f32 v[0:1], v[90:91], v[28:29], v[34:35] op_sel_hi:[1,0,1]
	v_pk_fma_f32 v[2:3], v[92:93], v[28:29], v[36:37] op_sel_hi:[1,0,1]
	s_cmp_eq_u32 s14, 0
	s_cbranch_scc1 .Lcons_skip_prev
	s_mov_b32 s2, 0xfffe0000
	s_mov_b32 s3, -1
	v_lshl_add_u64 v[148:149], v[44:45], 0, s[2:3]
	global_store_dword v[148:149], v147, off
.Lcons_skip_prev:
	v_pk_mul_f32 v[26:27], v[0:1], v[108:109]
	v_pk_mul_f32 v[30:31], v[116:117], v[102:103] op_sel:[0,1] op_sel_hi:[1,1]
	v_pk_mul_f32 v[32:33], v[118:119], v[102:103] op_sel:[0,1] op_sel_hi:[1,1]
	v_pk_fma_f32 v[26:27], v[2:3], v[110:111], v[26:27]
	v_pk_mul_f32 v[38:39], v[0:1], v[98:99]
	v_pk_fma_f32 v[34:35], v[0:1], v[104:105], v[30:31]
	v_add_f32_e32 v28, v26, v27
	v_pk_fma_f32 v[36:37], v[2:3], v[106:107], v[32:33]
	v_pk_fma_f32 v[38:39], v[2:3], v[100:101], v[38:39]
	v_add_f32_dpp v28, v28, v28 row_ror:8 row_mask:0xf bank_mask:0xf bound_ctrl:1
	ds_read_b128 v[86:89], v40 offset:9472
	ds_read_b128 v[94:97], v40 offset:9984
	v_add_f32_dpp v28, v28, v28 row_ror:4 row_mask:0xf bank_mask:0xf bound_ctrl:1
	v_add_f32_e32 v171, v38, v39
	ds_read2st64_b32 v[102:103], v52 offset0:41 offset1:47
	v_add_f32_dpp v28, v28, v28 row_ror:2 row_mask:0xf bank_mask:0xf bound_ctrl:1
	ds_read_b128 v[82:85], v40 offset:9216
	ds_read_b128 v[98:101], v40 offset:10240
	v_add_f32_dpp v28, v28, v28 row_ror:1 row_mask:0xf bank_mask:0xf bound_ctrl:1
	ds_read_b128 v[90:93], v40 offset:9728
	v_pk_fma_f32 v[0:1], v[112:113], v[28:29], v[34:35] op_sel_hi:[1,0,1]
	v_pk_fma_f32 v[2:3], v[114:115], v[28:29], v[36:37] op_sel_hi:[1,0,1]
	s_waitcnt lgkmcnt(6)
	v_pk_mul_f32 v[26:27], v[0:1], v[8:9]
	v_pk_mul_f32 v[30:31], v[16:17], v[24:25] op_sel_hi:[1,0]
	v_pk_mul_f32 v[32:33], v[18:19], v[24:25] op_sel_hi:[1,0]
	v_pk_fma_f32 v[26:27], v[2:3], v[10:11], v[26:27]
	v_pk_mul_f32 v[38:39], v[0:1], v[120:121]
	v_pk_fma_f32 v[34:35], v[0:1], v[4:5], v[30:31]
	v_add_f32_e32 v28, v26, v27
	v_pk_fma_f32 v[36:37], v[2:3], v[6:7], v[32:33]
	v_pk_fma_f32 v[38:39], v[2:3], v[122:123], v[38:39]
	v_add_f32_dpp v28, v28, v28 row_ror:8 row_mask:0xf bank_mask:0xf bound_ctrl:1
	ds_read_b128 v[108:111], v40 offset:11008
	ds_read_b128 v[116:119], v40 offset:11520
	v_add_f32_dpp v28, v28, v28 row_ror:4 row_mask:0xf bank_mask:0xf bound_ctrl:1
	v_add_f32_e32 v172, v38, v39
	ds_read_b128 v[104:107], v40 offset:10752
	v_add_f32_dpp v28, v28, v28 row_ror:2 row_mask:0xf bank_mask:0xf bound_ctrl:1
	ds_read_b128 v[120:123], v40 offset:11776
	ds_read_b128 v[112:115], v40 offset:11264
	v_add_f32_dpp v28, v28, v28 row_ror:1 row_mask:0xf bank_mask:0xf bound_ctrl:1
	v_pk_fma_f32 v[0:1], v[12:13], v[28:29], v[34:35] op_sel_hi:[1,0,1]
	v_pk_fma_f32 v[2:3], v[14:15], v[28:29], v[36:37] op_sel_hi:[1,0,1]
	v_pk_mul_f32 v[26:27], v[0:1], v[64:65]
	v_pk_mul_f32 v[30:31], v[72:73], v[24:25] op_sel:[0,1] op_sel_hi:[1,1]
	v_pk_mul_f32 v[32:33], v[74:75], v[24:25] op_sel:[0,1] op_sel_hi:[1,1]
	v_pk_fma_f32 v[26:27], v[2:3], v[66:67], v[26:27]
	v_pk_mul_f32 v[38:39], v[0:1], v[20:21]
	v_pk_fma_f32 v[34:35], v[0:1], v[60:61], v[30:31]
	v_add_f32_e32 v28, v26, v27
	v_pk_fma_f32 v[36:37], v[2:3], v[62:63], v[32:33]
	v_pk_fma_f32 v[38:39], v[2:3], v[22:23], v[38:39]
	v_add_f32_dpp v28, v28, v28 row_ror:8 row_mask:0xf bank_mask:0xf bound_ctrl:1
	ds_read_b128 v[8:11], v40 offset:12544
	ds_read_b128 v[16:19], v40 offset:13056
	v_add_f32_dpp v28, v28, v28 row_ror:4 row_mask:0xf bank_mask:0xf bound_ctrl:1
	v_add_f32_e32 v173, v38, v39
	ds_read2st64_b32 v[24:25], v52 offset0:53 offset1:59
	v_add_f32_dpp v28, v28, v28 row_ror:2 row_mask:0xf bank_mask:0xf bound_ctrl:1
	ds_read_b128 v[4:7], v40 offset:12288
	ds_read_b128 v[20:23], v40 offset:13312
	v_add_f32_dpp v28, v28, v28 row_ror:1 row_mask:0xf bank_mask:0xf bound_ctrl:1
	ds_read_b128 v[12:15], v40 offset:12800
	v_pk_fma_f32 v[0:1], v[68:69], v[28:29], v[34:35] op_sel_hi:[1,0,1]
	v_pk_fma_f32 v[2:3], v[70:71], v[28:29], v[36:37] op_sel_hi:[1,0,1]
	s_waitcnt lgkmcnt(6)
	v_pk_mul_f32 v[26:27], v[0:1], v[86:87]
	v_pk_mul_f32 v[30:31], v[94:95], v[102:103] op_sel_hi:[1,0]
	v_pk_mul_f32 v[32:33], v[96:97], v[102:103] op_sel_hi:[1,0]
	v_pk_fma_f32 v[26:27], v[2:3], v[88:89], v[26:27]
	v_pk_mul_f32 v[38:39], v[0:1], v[76:77]
	v_pk_fma_f32 v[34:35], v[0:1], v[82:83], v[30:31]
	v_add_f32_e32 v28, v26, v27
	v_pk_fma_f32 v[36:37], v[2:3], v[84:85], v[32:33]
	v_pk_fma_f32 v[38:39], v[2:3], v[78:79], v[38:39]
	v_add_f32_dpp v28, v28, v28 row_ror:8 row_mask:0xf bank_mask:0xf bound_ctrl:1
	ds_read_b128 v[64:67], v40 offset:14080
	ds_read_b128 v[72:75], v40 offset:14592
	v_add_f32_dpp v28, v28, v28 row_ror:4 row_mask:0xf bank_mask:0xf bound_ctrl:1
	v_add_f32_e32 v174, v38, v39
	ds_read_b128 v[60:63], v40 offset:13824
	v_add_f32_dpp v28, v28, v28 row_ror:2 row_mask:0xf bank_mask:0xf bound_ctrl:1
	ds_read_b128 v[76:79], v40 offset:14848
	ds_read_b128 v[68:71], v40 offset:14336
	v_add_f32_dpp v28, v28, v28 row_ror:1 row_mask:0xf bank_mask:0xf bound_ctrl:1
	v_pk_fma_f32 v[0:1], v[90:91], v[28:29], v[34:35] op_sel_hi:[1,0,1]
	v_pk_fma_f32 v[2:3], v[92:93], v[28:29], v[36:37] op_sel_hi:[1,0,1]
	v_pk_mul_f32 v[26:27], v[0:1], v[108:109]
	v_pk_mul_f32 v[30:31], v[116:117], v[102:103] op_sel:[0,1] op_sel_hi:[1,1]
	v_pk_mul_f32 v[32:33], v[118:119], v[102:103] op_sel:[0,1] op_sel_hi:[1,1]
	v_pk_fma_f32 v[26:27], v[2:3], v[110:111], v[26:27]
	v_pk_mul_f32 v[38:39], v[0:1], v[98:99]
	v_pk_fma_f32 v[34:35], v[0:1], v[104:105], v[30:31]
	v_add_f32_e32 v28, v26, v27
	v_pk_fma_f32 v[36:37], v[2:3], v[106:107], v[32:33]
	v_pk_fma_f32 v[38:39], v[2:3], v[100:101], v[38:39]
	v_add_f32_dpp v28, v28, v28 row_ror:8 row_mask:0xf bank_mask:0xf bound_ctrl:1
	ds_read_b128 v[86:89], v40 offset:15616
	ds_read_b128 v[94:97], v40 offset:16128
	v_add_f32_dpp v28, v28, v28 row_ror:4 row_mask:0xf bank_mask:0xf bound_ctrl:1
	v_add_f32_e32 v175, v38, v39
	ds_read2st64_b32 v[102:103], v52 offset0:65 offset1:71
	v_add_f32_dpp v28, v28, v28 row_ror:2 row_mask:0xf bank_mask:0xf bound_ctrl:1
	ds_read_b128 v[82:85], v40 offset:15360
	ds_read_b128 v[98:101], v40 offset:16384
	v_add_f32_dpp v28, v28, v28 row_ror:1 row_mask:0xf bank_mask:0xf bound_ctrl:1
	ds_read_b128 v[90:93], v40 offset:15872
	v_pk_fma_f32 v[0:1], v[112:113], v[28:29], v[34:35] op_sel_hi:[1,0,1]
	v_pk_fma_f32 v[2:3], v[114:115], v[28:29], v[36:37] op_sel_hi:[1,0,1]
	s_waitcnt lgkmcnt(6)
	v_pk_mul_f32 v[26:27], v[0:1], v[8:9]
	v_pk_mul_f32 v[30:31], v[16:17], v[24:25] op_sel_hi:[1,0]
	v_pk_mul_f32 v[32:33], v[18:19], v[24:25] op_sel_hi:[1,0]
	v_pk_fma_f32 v[26:27], v[2:3], v[10:11], v[26:27]
	v_pk_mul_f32 v[38:39], v[0:1], v[120:121]
	v_pk_fma_f32 v[34:35], v[0:1], v[4:5], v[30:31]
	v_add_f32_e32 v28, v26, v27
	v_pk_fma_f32 v[36:37], v[2:3], v[6:7], v[32:33]
	v_pk_fma_f32 v[38:39], v[2:3], v[122:123], v[38:39]
	v_add_f32_dpp v28, v28, v28 row_ror:8 row_mask:0xf bank_mask:0xf bound_ctrl:1
	ds_read_b128 v[108:111], v40 offset:17152
	ds_read_b128 v[116:119], v40 offset:17664
	v_add_f32_dpp v28, v28, v28 row_ror:4 row_mask:0xf bank_mask:0xf bound_ctrl:1
	v_add_f32_e32 v176, v38, v39
	ds_read_b128 v[104:107], v40 offset:16896
	v_add_f32_dpp v28, v28, v28 row_ror:2 row_mask:0xf bank_mask:0xf bound_ctrl:1
	ds_read_b128 v[120:123], v40 offset:17920
	ds_read_b128 v[112:115], v40 offset:17408
	v_add_f32_dpp v28, v28, v28 row_ror:1 row_mask:0xf bank_mask:0xf bound_ctrl:1
	v_pk_fma_f32 v[0:1], v[12:13], v[28:29], v[34:35] op_sel_hi:[1,0,1]
	v_pk_fma_f32 v[2:3], v[14:15], v[28:29], v[36:37] op_sel_hi:[1,0,1]
	v_pk_mul_f32 v[26:27], v[0:1], v[64:65]
	v_pk_mul_f32 v[30:31], v[72:73], v[24:25] op_sel:[0,1] op_sel_hi:[1,1]
	v_pk_mul_f32 v[32:33], v[74:75], v[24:25] op_sel:[0,1] op_sel_hi:[1,1]
	v_pk_fma_f32 v[26:27], v[2:3], v[66:67], v[26:27]
	v_pk_mul_f32 v[38:39], v[0:1], v[20:21]
	v_pk_fma_f32 v[34:35], v[0:1], v[60:61], v[30:31]
	v_add_f32_e32 v28, v26, v27
	v_pk_fma_f32 v[36:37], v[2:3], v[62:63], v[32:33]
	v_pk_fma_f32 v[38:39], v[2:3], v[22:23], v[38:39]
	v_add_f32_dpp v28, v28, v28 row_ror:8 row_mask:0xf bank_mask:0xf bound_ctrl:1
	ds_read_b128 v[8:11], v40 offset:18688
	ds_read_b128 v[16:19], v40 offset:19200
	v_add_f32_dpp v28, v28, v28 row_ror:4 row_mask:0xf bank_mask:0xf bound_ctrl:1
	v_add_f32_e32 v177, v38, v39
	ds_read2st64_b32 v[24:25], v52 offset0:77 offset1:83
	v_add_f32_dpp v28, v28, v28 row_ror:2 row_mask:0xf bank_mask:0xf bound_ctrl:1
	ds_read_b128 v[4:7], v40 offset:18432
	ds_read_b128 v[20:23], v40 offset:19456
	v_add_f32_dpp v28, v28, v28 row_ror:1 row_mask:0xf bank_mask:0xf bound_ctrl:1
	ds_read_b128 v[12:15], v40 offset:18944
	v_pk_fma_f32 v[0:1], v[68:69], v[28:29], v[34:35] op_sel_hi:[1,0,1]
	v_pk_fma_f32 v[2:3], v[70:71], v[28:29], v[36:37] op_sel_hi:[1,0,1]
	s_waitcnt lgkmcnt(6)
	v_pk_mul_f32 v[26:27], v[0:1], v[86:87]
	v_pk_mul_f32 v[30:31], v[94:95], v[102:103] op_sel_hi:[1,0]
	v_pk_mul_f32 v[32:33], v[96:97], v[102:103] op_sel_hi:[1,0]
	v_pk_fma_f32 v[26:27], v[2:3], v[88:89], v[26:27]
	v_pk_mul_f32 v[38:39], v[0:1], v[76:77]
	v_pk_fma_f32 v[34:35], v[0:1], v[82:83], v[30:31]
	v_add_f32_e32 v28, v26, v27
	v_pk_fma_f32 v[36:37], v[2:3], v[84:85], v[32:33]
	v_pk_fma_f32 v[38:39], v[2:3], v[78:79], v[38:39]
	v_add_f32_dpp v28, v28, v28 row_ror:8 row_mask:0xf bank_mask:0xf bound_ctrl:1
	ds_read_b128 v[64:67], v40 offset:20224
	ds_read_b128 v[72:75], v40 offset:20736
	v_add_f32_dpp v28, v28, v28 row_ror:4 row_mask:0xf bank_mask:0xf bound_ctrl:1
	v_add_f32_e32 v178, v38, v39
	ds_read_b128 v[60:63], v40 offset:19968
	v_add_f32_dpp v28, v28, v28 row_ror:2 row_mask:0xf bank_mask:0xf bound_ctrl:1
	ds_read_b128 v[76:79], v40 offset:20992
	ds_read_b128 v[68:71], v40 offset:20480
	v_add_f32_dpp v28, v28, v28 row_ror:1 row_mask:0xf bank_mask:0xf bound_ctrl:1
	v_pk_fma_f32 v[0:1], v[90:91], v[28:29], v[34:35] op_sel_hi:[1,0,1]
	v_pk_fma_f32 v[2:3], v[92:93], v[28:29], v[36:37] op_sel_hi:[1,0,1]
	v_pk_mul_f32 v[26:27], v[0:1], v[108:109]
	v_pk_mul_f32 v[30:31], v[116:117], v[102:103] op_sel:[0,1] op_sel_hi:[1,1]
	v_pk_mul_f32 v[32:33], v[118:119], v[102:103] op_sel:[0,1] op_sel_hi:[1,1]
	v_pk_fma_f32 v[26:27], v[2:3], v[110:111], v[26:27]
	v_pk_mul_f32 v[38:39], v[0:1], v[98:99]
	v_pk_fma_f32 v[34:35], v[0:1], v[104:105], v[30:31]
	v_add_f32_e32 v28, v26, v27
	v_pk_fma_f32 v[36:37], v[2:3], v[106:107], v[32:33]
	v_pk_fma_f32 v[38:39], v[2:3], v[100:101], v[38:39]
	v_add_f32_dpp v28, v28, v28 row_ror:8 row_mask:0xf bank_mask:0xf bound_ctrl:1
	ds_read_b128 v[86:89], v40 offset:21760
	ds_read_b128 v[94:97], v40 offset:22272
	v_add_f32_dpp v28, v28, v28 row_ror:4 row_mask:0xf bank_mask:0xf bound_ctrl:1
	v_add_f32_e32 v179, v38, v39
	ds_read2st64_b32 v[102:103], v52 offset0:89 offset1:95
	v_add_f32_dpp v28, v28, v28 row_ror:2 row_mask:0xf bank_mask:0xf bound_ctrl:1
	ds_read_b128 v[82:85], v40 offset:21504
	ds_read_b128 v[98:101], v40 offset:22528
	v_add_f32_dpp v28, v28, v28 row_ror:1 row_mask:0xf bank_mask:0xf bound_ctrl:1
	ds_read_b128 v[90:93], v40 offset:22016
	v_pk_fma_f32 v[0:1], v[112:113], v[28:29], v[34:35] op_sel_hi:[1,0,1]
	v_pk_fma_f32 v[2:3], v[114:115], v[28:29], v[36:37] op_sel_hi:[1,0,1]
	s_waitcnt lgkmcnt(6)
	v_pk_mul_f32 v[26:27], v[0:1], v[8:9]
	v_pk_mul_f32 v[30:31], v[16:17], v[24:25] op_sel_hi:[1,0]
	v_pk_mul_f32 v[32:33], v[18:19], v[24:25] op_sel_hi:[1,0]
	v_pk_fma_f32 v[26:27], v[2:3], v[10:11], v[26:27]
	v_pk_mul_f32 v[38:39], v[0:1], v[120:121]
	v_pk_fma_f32 v[34:35], v[0:1], v[4:5], v[30:31]
	v_add_f32_e32 v28, v26, v27
	v_pk_fma_f32 v[36:37], v[2:3], v[6:7], v[32:33]
	v_pk_fma_f32 v[38:39], v[2:3], v[122:123], v[38:39]
	v_add_f32_dpp v28, v28, v28 row_ror:8 row_mask:0xf bank_mask:0xf bound_ctrl:1
	ds_read_b128 v[108:111], v40 offset:23296
	ds_read_b128 v[116:119], v40 offset:23808
	v_add_f32_dpp v28, v28, v28 row_ror:4 row_mask:0xf bank_mask:0xf bound_ctrl:1
	v_add_f32_e32 v180, v38, v39
	ds_read_b128 v[104:107], v40 offset:23040
	v_add_f32_dpp v28, v28, v28 row_ror:2 row_mask:0xf bank_mask:0xf bound_ctrl:1
	ds_read_b128 v[120:123], v40 offset:24064
	ds_read_b128 v[112:115], v40 offset:23552
	v_add_f32_dpp v28, v28, v28 row_ror:1 row_mask:0xf bank_mask:0xf bound_ctrl:1
	v_pk_fma_f32 v[0:1], v[12:13], v[28:29], v[34:35] op_sel_hi:[1,0,1]
	v_pk_fma_f32 v[2:3], v[14:15], v[28:29], v[36:37] op_sel_hi:[1,0,1]
	v_pk_mul_f32 v[26:27], v[0:1], v[64:65]
	v_pk_mul_f32 v[30:31], v[72:73], v[24:25] op_sel:[0,1] op_sel_hi:[1,1]
	v_pk_mul_f32 v[32:33], v[74:75], v[24:25] op_sel:[0,1] op_sel_hi:[1,1]
	v_pk_fma_f32 v[26:27], v[2:3], v[66:67], v[26:27]
	v_pk_mul_f32 v[38:39], v[0:1], v[20:21]
	v_pk_fma_f32 v[34:35], v[0:1], v[60:61], v[30:31]
	v_add_f32_e32 v28, v26, v27
	v_pk_fma_f32 v[36:37], v[2:3], v[62:63], v[32:33]
	v_pk_fma_f32 v[38:39], v[2:3], v[22:23], v[38:39]
	v_add_f32_dpp v28, v28, v28 row_ror:8 row_mask:0xf bank_mask:0xf bound_ctrl:1
	ds_read_b128 v[8:11], v40 offset:24832
	ds_read_b128 v[16:19], v40 offset:25344
	v_add_f32_dpp v28, v28, v28 row_ror:4 row_mask:0xf bank_mask:0xf bound_ctrl:1
	v_add_f32_e32 v181, v38, v39
	ds_read2st64_b32 v[24:25], v52 offset0:101 offset1:107
	v_add_f32_dpp v28, v28, v28 row_ror:2 row_mask:0xf bank_mask:0xf bound_ctrl:1
	ds_read_b128 v[4:7], v40 offset:24576
	ds_read_b128 v[20:23], v40 offset:25600
	v_add_f32_dpp v28, v28, v28 row_ror:1 row_mask:0xf bank_mask:0xf bound_ctrl:1
	ds_read_b128 v[12:15], v40 offset:25088
	v_pk_fma_f32 v[0:1], v[68:69], v[28:29], v[34:35] op_sel_hi:[1,0,1]
	v_pk_fma_f32 v[2:3], v[70:71], v[28:29], v[36:37] op_sel_hi:[1,0,1]
	s_waitcnt lgkmcnt(6)
	v_pk_mul_f32 v[26:27], v[0:1], v[86:87]
	v_pk_mul_f32 v[30:31], v[94:95], v[102:103] op_sel_hi:[1,0]
	v_pk_mul_f32 v[32:33], v[96:97], v[102:103] op_sel_hi:[1,0]
	v_pk_fma_f32 v[26:27], v[2:3], v[88:89], v[26:27]
	v_pk_mul_f32 v[38:39], v[0:1], v[76:77]
	v_pk_fma_f32 v[34:35], v[0:1], v[82:83], v[30:31]
	v_add_f32_e32 v28, v26, v27
	v_pk_fma_f32 v[36:37], v[2:3], v[84:85], v[32:33]
	v_pk_fma_f32 v[38:39], v[2:3], v[78:79], v[38:39]
	v_add_f32_dpp v28, v28, v28 row_ror:8 row_mask:0xf bank_mask:0xf bound_ctrl:1
	ds_read_b128 v[64:67], v40 offset:26368
	ds_read_b128 v[72:75], v40 offset:26880
	v_add_f32_dpp v28, v28, v28 row_ror:4 row_mask:0xf bank_mask:0xf bound_ctrl:1
	v_add_f32_e32 v182, v38, v39
	ds_read_b128 v[60:63], v40 offset:26112
	v_add_f32_dpp v28, v28, v28 row_ror:2 row_mask:0xf bank_mask:0xf bound_ctrl:1
	ds_read_b128 v[76:79], v40 offset:27136
	ds_read_b128 v[68:71], v40 offset:26624
	v_add_f32_dpp v28, v28, v28 row_ror:1 row_mask:0xf bank_mask:0xf bound_ctrl:1
	v_pk_fma_f32 v[0:1], v[90:91], v[28:29], v[34:35] op_sel_hi:[1,0,1]
	v_pk_fma_f32 v[2:3], v[92:93], v[28:29], v[36:37] op_sel_hi:[1,0,1]
	v_pk_mul_f32 v[26:27], v[0:1], v[108:109]
	v_pk_mul_f32 v[30:31], v[116:117], v[102:103] op_sel:[0,1] op_sel_hi:[1,1]
	v_pk_mul_f32 v[32:33], v[118:119], v[102:103] op_sel:[0,1] op_sel_hi:[1,1]
	v_pk_fma_f32 v[26:27], v[2:3], v[110:111], v[26:27]
	v_pk_mul_f32 v[38:39], v[0:1], v[98:99]
	v_pk_fma_f32 v[34:35], v[0:1], v[104:105], v[30:31]
	v_add_f32_e32 v28, v26, v27
	v_pk_fma_f32 v[36:37], v[2:3], v[106:107], v[32:33]
	v_pk_fma_f32 v[38:39], v[2:3], v[100:101], v[38:39]
	v_add_f32_dpp v28, v28, v28 row_ror:8 row_mask:0xf bank_mask:0xf bound_ctrl:1
	ds_read_b128 v[86:89], v40 offset:27904
	ds_read_b128 v[94:97], v40 offset:28416
	v_add_f32_dpp v28, v28, v28 row_ror:4 row_mask:0xf bank_mask:0xf bound_ctrl:1
	v_add_f32_e32 v183, v38, v39
	ds_read2st64_b32 v[102:103], v52 offset0:113 offset1:119
	v_add_f32_dpp v28, v28, v28 row_ror:2 row_mask:0xf bank_mask:0xf bound_ctrl:1
	ds_read_b128 v[82:85], v40 offset:27648
	ds_read_b128 v[98:101], v40 offset:28672
	v_add_f32_dpp v28, v28, v28 row_ror:1 row_mask:0xf bank_mask:0xf bound_ctrl:1
	ds_read_b128 v[90:93], v40 offset:28160
	v_pk_fma_f32 v[0:1], v[112:113], v[28:29], v[34:35] op_sel_hi:[1,0,1]
	v_pk_fma_f32 v[2:3], v[114:115], v[28:29], v[36:37] op_sel_hi:[1,0,1]
	s_waitcnt lgkmcnt(6)
	v_pk_mul_f32 v[26:27], v[0:1], v[8:9]
	v_pk_mul_f32 v[30:31], v[16:17], v[24:25] op_sel_hi:[1,0]
	v_pk_mul_f32 v[32:33], v[18:19], v[24:25] op_sel_hi:[1,0]
	v_pk_fma_f32 v[26:27], v[2:3], v[10:11], v[26:27]
	v_pk_mul_f32 v[38:39], v[0:1], v[120:121]
	v_pk_fma_f32 v[34:35], v[0:1], v[4:5], v[30:31]
	v_add_f32_e32 v28, v26, v27
	v_pk_fma_f32 v[36:37], v[2:3], v[6:7], v[32:33]
	v_pk_fma_f32 v[38:39], v[2:3], v[122:123], v[38:39]
	v_add_f32_dpp v28, v28, v28 row_ror:8 row_mask:0xf bank_mask:0xf bound_ctrl:1
	ds_read_b128 v[108:111], v40 offset:29440
	ds_read_b128 v[116:119], v40 offset:29952
	v_add_f32_dpp v28, v28, v28 row_ror:4 row_mask:0xf bank_mask:0xf bound_ctrl:1
	v_add_f32_e32 v184, v38, v39
	ds_read_b128 v[104:107], v40 offset:29184
	v_add_f32_dpp v28, v28, v28 row_ror:2 row_mask:0xf bank_mask:0xf bound_ctrl:1
	ds_read_b128 v[120:123], v40 offset:30208
	ds_read_b128 v[112:115], v40 offset:29696
	v_add_f32_dpp v28, v28, v28 row_ror:1 row_mask:0xf bank_mask:0xf bound_ctrl:1
	v_pk_fma_f32 v[0:1], v[12:13], v[28:29], v[34:35] op_sel_hi:[1,0,1]
	v_pk_fma_f32 v[2:3], v[14:15], v[28:29], v[36:37] op_sel_hi:[1,0,1]
	v_pk_mul_f32 v[26:27], v[0:1], v[64:65]
	v_pk_mul_f32 v[30:31], v[72:73], v[24:25] op_sel:[0,1] op_sel_hi:[1,1]
	v_pk_mul_f32 v[32:33], v[74:75], v[24:25] op_sel:[0,1] op_sel_hi:[1,1]
	v_pk_fma_f32 v[26:27], v[2:3], v[66:67], v[26:27]
	v_pk_mul_f32 v[38:39], v[0:1], v[20:21]
	v_pk_fma_f32 v[34:35], v[0:1], v[60:61], v[30:31]
	v_add_f32_e32 v28, v26, v27
	v_pk_fma_f32 v[36:37], v[2:3], v[62:63], v[32:33]
	v_pk_fma_f32 v[38:39], v[2:3], v[22:23], v[38:39]
	v_add_f32_dpp v28, v28, v28 row_ror:8 row_mask:0xf bank_mask:0xf bound_ctrl:1
	ds_read_b128 v[8:11], v40 offset:30976
	ds_read_b128 v[16:19], v40 offset:31488
	v_add_f32_dpp v28, v28, v28 row_ror:4 row_mask:0xf bank_mask:0xf bound_ctrl:1
	v_add_f32_e32 v46, v38, v39
	ds_read2st64_b32 v[24:25], v52 offset0:125 offset1:131
	v_add_f32_dpp v28, v28, v28 row_ror:2 row_mask:0xf bank_mask:0xf bound_ctrl:1
	ds_read_b128 v[4:7], v40 offset:30720
	ds_read_b128 v[20:23], v40 offset:31744
	v_add_f32_dpp v28, v28, v28 row_ror:1 row_mask:0xf bank_mask:0xf bound_ctrl:1
	ds_read_b128 v[12:15], v40 offset:31232
	v_add_f32_dpp v185, v169, v169 row_mirror row_mask:0xf bank_mask:0x3
	v_pk_fma_f32 v[0:1], v[68:69], v[28:29], v[34:35] op_sel_hi:[1,0,1]
	v_pk_fma_f32 v[2:3], v[70:71], v[28:29], v[36:37] op_sel_hi:[1,0,1]
	v_add_f32_dpp v185, v177, v177 row_mirror row_mask:0xf bank_mask:0xc
	v_add_f32_dpp v186, v170, v170 row_mirror row_mask:0xf bank_mask:0x3
	s_waitcnt lgkmcnt(6)
	v_pk_mul_f32 v[26:27], v[0:1], v[86:87]
	v_pk_mul_f32 v[30:31], v[94:95], v[102:103] op_sel_hi:[1,0]
	v_pk_mul_f32 v[32:33], v[96:97], v[102:103] op_sel_hi:[1,0]
	v_pk_fma_f32 v[26:27], v[2:3], v[88:89], v[26:27]
	v_pk_mul_f32 v[38:39], v[0:1], v[76:77]
	v_pk_fma_f32 v[34:35], v[0:1], v[82:83], v[30:31]
	v_add_f32_e32 v28, v26, v27
	v_pk_fma_f32 v[36:37], v[2:3], v[84:85], v[32:33]
	v_pk_fma_f32 v[38:39], v[2:3], v[78:79], v[38:39]
	v_add_f32_dpp v28, v28, v28 row_ror:8 row_mask:0xf bank_mask:0xf bound_ctrl:1
	ds_read_b128 v[64:67], v40 offset:32512
	ds_read_b128 v[72:75], v40 offset:33024
	v_add_f32_dpp v28, v28, v28 row_ror:4 row_mask:0xf bank_mask:0xf bound_ctrl:1
	v_add_f32_e32 v47, v38, v39
	ds_read_b128 v[60:63], v40 offset:32256
	v_add_f32_dpp v28, v28, v28 row_ror:2 row_mask:0xf bank_mask:0xf bound_ctrl:1
	ds_read_b128 v[76:79], v40 offset:33280
	ds_read_b128 v[68:71], v40 offset:32768
	v_add_f32_dpp v28, v28, v28 row_ror:1 row_mask:0xf bank_mask:0xf bound_ctrl:1
	v_add_f32_dpp v186, v178, v178 row_mirror row_mask:0xf bank_mask:0xc
	v_add_f32_dpp v187, v171, v171 row_mirror row_mask:0xf bank_mask:0x3
	v_pk_fma_f32 v[0:1], v[90:91], v[28:29], v[34:35] op_sel_hi:[1,0,1]
	v_pk_fma_f32 v[2:3], v[92:93], v[28:29], v[36:37] op_sel_hi:[1,0,1]
	v_add_f32_dpp v187, v179, v179 row_mirror row_mask:0xf bank_mask:0xc
	v_add_f32_dpp v188, v172, v172 row_mirror row_mask:0xf bank_mask:0x3
	v_pk_mul_f32 v[26:27], v[0:1], v[108:109]
	v_pk_mul_f32 v[30:31], v[116:117], v[102:103] op_sel:[0,1] op_sel_hi:[1,1]
	v_pk_mul_f32 v[32:33], v[118:119], v[102:103] op_sel:[0,1] op_sel_hi:[1,1]
	v_pk_fma_f32 v[26:27], v[2:3], v[110:111], v[26:27]
	v_pk_mul_f32 v[38:39], v[0:1], v[98:99]
	v_pk_fma_f32 v[34:35], v[0:1], v[104:105], v[30:31]
	v_add_f32_e32 v28, v26, v27
	v_pk_fma_f32 v[36:37], v[2:3], v[106:107], v[32:33]
	v_pk_fma_f32 v[38:39], v[2:3], v[100:101], v[38:39]
	v_add_f32_dpp v28, v28, v28 row_ror:8 row_mask:0xf bank_mask:0xf bound_ctrl:1
	ds_read_b128 v[86:89], v40 offset:34048
	ds_read_b128 v[94:97], v40 offset:34560
	v_add_f32_dpp v28, v28, v28 row_ror:4 row_mask:0xf bank_mask:0xf bound_ctrl:1
	v_add_f32_e32 v48, v38, v39
	ds_read2st64_b32 v[102:103], v52 offset0:137 offset1:143
	v_add_f32_dpp v28, v28, v28 row_ror:2 row_mask:0xf bank_mask:0xf bound_ctrl:1
	ds_read_b128 v[82:85], v40 offset:33792
	ds_read_b128 v[98:101], v40 offset:34816
	v_add_f32_dpp v28, v28, v28 row_ror:1 row_mask:0xf bank_mask:0xf bound_ctrl:1
	ds_read_b128 v[90:93], v40 offset:34304
	v_add_f32_dpp v188, v180, v180 row_mirror row_mask:0xf bank_mask:0xc
	v_pk_fma_f32 v[0:1], v[112:113], v[28:29], v[34:35] op_sel_hi:[1,0,1]
	v_pk_fma_f32 v[2:3], v[114:115], v[28:29], v[36:37] op_sel_hi:[1,0,1]
	v_add_f32_dpp v189, v173, v173 row_mirror row_mask:0xf bank_mask:0x3
	v_add_f32_dpp v190, v174, v174 row_mirror row_mask:0xf bank_mask:0x3
	s_waitcnt lgkmcnt(6)
	v_pk_mul_f32 v[26:27], v[0:1], v[8:9]
	v_pk_mul_f32 v[30:31], v[16:17], v[24:25] op_sel_hi:[1,0]
	v_pk_mul_f32 v[32:33], v[18:19], v[24:25] op_sel_hi:[1,0]
	v_pk_fma_f32 v[26:27], v[2:3], v[10:11], v[26:27]
	v_pk_mul_f32 v[38:39], v[0:1], v[120:121]
	v_pk_fma_f32 v[34:35], v[0:1], v[4:5], v[30:31]
	v_add_f32_e32 v28, v26, v27
	v_pk_fma_f32 v[36:37], v[2:3], v[6:7], v[32:33]
	v_pk_fma_f32 v[38:39], v[2:3], v[122:123], v[38:39]
	v_add_f32_dpp v28, v28, v28 row_ror:8 row_mask:0xf bank_mask:0xf bound_ctrl:1
	ds_read_b128 v[108:111], v40 offset:35584
	ds_read_b128 v[116:119], v40 offset:36096
	v_add_f32_dpp v28, v28, v28 row_ror:4 row_mask:0xf bank_mask:0xf bound_ctrl:1
	v_add_f32_e32 v49, v38, v39
	ds_read_b128 v[104:107], v40 offset:35328
	v_add_f32_dpp v28, v28, v28 row_ror:2 row_mask:0xf bank_mask:0xf bound_ctrl:1
	ds_read_b128 v[120:123], v40 offset:36352
	ds_read_b128 v[112:115], v40 offset:35840
	v_add_f32_dpp v28, v28, v28 row_ror:1 row_mask:0xf bank_mask:0xf bound_ctrl:1
	v_add_f32_dpp v189, v181, v181 row_mirror row_mask:0xf bank_mask:0xc
	v_add_f32_dpp v190, v182, v182 row_mirror row_mask:0xf bank_mask:0xc
	v_pk_fma_f32 v[0:1], v[12:13], v[28:29], v[34:35] op_sel_hi:[1,0,1]
	v_pk_fma_f32 v[2:3], v[14:15], v[28:29], v[36:37] op_sel_hi:[1,0,1]
	v_add_f32_dpp v191, v175, v175 row_mirror row_mask:0xf bank_mask:0x3
	v_add_f32_dpp v192, v176, v176 row_mirror row_mask:0xf bank_mask:0x3
	v_pk_mul_f32 v[26:27], v[0:1], v[64:65]
	v_pk_mul_f32 v[30:31], v[72:73], v[24:25] op_sel:[0,1] op_sel_hi:[1,1]
	v_pk_mul_f32 v[32:33], v[74:75], v[24:25] op_sel:[0,1] op_sel_hi:[1,1]
	v_pk_fma_f32 v[26:27], v[2:3], v[66:67], v[26:27]
	v_pk_mul_f32 v[38:39], v[0:1], v[20:21]
	v_pk_fma_f32 v[34:35], v[0:1], v[60:61], v[30:31]
	v_add_f32_e32 v28, v26, v27
	v_pk_fma_f32 v[36:37], v[2:3], v[62:63], v[32:33]
	v_pk_fma_f32 v[38:39], v[2:3], v[22:23], v[38:39]
	v_add_f32_dpp v28, v28, v28 row_ror:8 row_mask:0xf bank_mask:0xf bound_ctrl:1
	ds_read_b128 v[8:11], v40 offset:37120
	ds_read_b128 v[16:19], v40 offset:37632
	v_add_f32_dpp v28, v28, v28 row_ror:4 row_mask:0xf bank_mask:0xf bound_ctrl:1
	v_add_f32_e32 v50, v38, v39
	ds_read2st64_b32 v[24:25], v52 offset0:149 offset1:155
	v_add_f32_dpp v28, v28, v28 row_ror:2 row_mask:0xf bank_mask:0xf bound_ctrl:1
	ds_read_b128 v[4:7], v40 offset:36864
	ds_read_b128 v[20:23], v40 offset:37888
	v_add_f32_dpp v28, v28, v28 row_ror:1 row_mask:0xf bank_mask:0xf bound_ctrl:1
	ds_read_b128 v[12:15], v40 offset:37376
	v_add_f32_dpp v191, v183, v183 row_mirror row_mask:0xf bank_mask:0xc
	v_pk_fma_f32 v[0:1], v[68:69], v[28:29], v[34:35] op_sel_hi:[1,0,1]
	v_pk_fma_f32 v[2:3], v[70:71], v[28:29], v[36:37] op_sel_hi:[1,0,1]
	v_add_f32_dpp v192, v184, v184 row_mirror row_mask:0xf bank_mask:0xc
	v_add_f32_dpp v141, v185, v185 row_half_mirror row_mask:0xf bank_mask:0x5
	s_waitcnt lgkmcnt(6)
	v_pk_mul_f32 v[26:27], v[0:1], v[86:87]
	v_pk_mul_f32 v[30:31], v[94:95], v[102:103] op_sel_hi:[1,0]
	v_pk_mul_f32 v[32:33], v[96:97], v[102:103] op_sel_hi:[1,0]
	v_pk_fma_f32 v[26:27], v[2:3], v[88:89], v[26:27]
	v_pk_mul_f32 v[38:39], v[0:1], v[76:77]
	v_pk_fma_f32 v[34:35], v[0:1], v[82:83], v[30:31]
	v_add_f32_e32 v28, v26, v27
	v_pk_fma_f32 v[36:37], v[2:3], v[84:85], v[32:33]
	v_pk_fma_f32 v[38:39], v[2:3], v[78:79], v[38:39]
	v_add_f32_dpp v28, v28, v28 row_ror:8 row_mask:0xf bank_mask:0xf bound_ctrl:1
	ds_read_b128 v[64:67], v40 offset:38656
	ds_read_b128 v[72:75], v40 offset:39168
	v_add_f32_dpp v28, v28, v28 row_ror:4 row_mask:0xf bank_mask:0xf bound_ctrl:1
	v_add_f32_e32 v51, v38, v39
	ds_read_b128 v[60:63], v40 offset:38400
	v_add_f32_dpp v28, v28, v28 row_ror:2 row_mask:0xf bank_mask:0xf bound_ctrl:1
	ds_read_b128 v[76:79], v40 offset:39424
	ds_read_b128 v[68:71], v40 offset:38912
	v_add_f32_dpp v28, v28, v28 row_ror:1 row_mask:0xf bank_mask:0xf bound_ctrl:1
	v_add_f32_dpp v141, v189, v189 row_half_mirror row_mask:0xf bank_mask:0xa
	v_add_f32_dpp v142, v186, v186 row_half_mirror row_mask:0xf bank_mask:0x5
	v_pk_fma_f32 v[0:1], v[90:91], v[28:29], v[34:35] op_sel_hi:[1,0,1]
	v_pk_fma_f32 v[2:3], v[92:93], v[28:29], v[36:37] op_sel_hi:[1,0,1]
	v_add_f32_dpp v142, v190, v190 row_half_mirror row_mask:0xf bank_mask:0xa
	v_add_f32_dpp v143, v187, v187 row_half_mirror row_mask:0xf bank_mask:0x5
	v_pk_mul_f32 v[26:27], v[0:1], v[108:109]
	v_pk_mul_f32 v[30:31], v[116:117], v[102:103] op_sel:[0,1] op_sel_hi:[1,1]
	v_pk_mul_f32 v[32:33], v[118:119], v[102:103] op_sel:[0,1] op_sel_hi:[1,1]
	v_pk_fma_f32 v[26:27], v[2:3], v[110:111], v[26:27]
	v_pk_mul_f32 v[38:39], v[0:1], v[98:99]
	v_pk_fma_f32 v[34:35], v[0:1], v[104:105], v[30:31]
	v_add_f32_e32 v28, v26, v27
	v_pk_fma_f32 v[36:37], v[2:3], v[106:107], v[32:33]
	v_pk_fma_f32 v[38:39], v[2:3], v[100:101], v[38:39]
	v_add_f32_dpp v28, v28, v28 row_ror:8 row_mask:0xf bank_mask:0xf bound_ctrl:1
	ds_read_b128 v[86:89], v40 offset:40192
	ds_read_b128 v[94:97], v40 offset:40704
	v_add_f32_dpp v28, v28, v28 row_ror:4 row_mask:0xf bank_mask:0xf bound_ctrl:1
	v_add_f32_e32 v53, v38, v39
	ds_read2st64_b32 v[102:103], v52 offset0:161 offset1:167
	v_add_f32_dpp v28, v28, v28 row_ror:2 row_mask:0xf bank_mask:0xf bound_ctrl:1
	ds_read_b128 v[82:85], v40 offset:39936
	ds_read_b128 v[98:101], v40 offset:40960
	v_add_f32_dpp v28, v28, v28 row_ror:1 row_mask:0xf bank_mask:0xf bound_ctrl:1
	ds_read_b128 v[90:93], v40 offset:40448
	v_add_f32_dpp v143, v191, v191 row_half_mirror row_mask:0xf bank_mask:0xa
	v_pk_fma_f32 v[0:1], v[112:113], v[28:29], v[34:35] op_sel_hi:[1,0,1]
	v_pk_fma_f32 v[2:3], v[114:115], v[28:29], v[36:37] op_sel_hi:[1,0,1]
	v_add_f32_dpp v144, v188, v188 row_half_mirror row_mask:0xf bank_mask:0x5
	v_cndmask_b32_e64 v145, v143, v141, s[8:9]
	s_waitcnt lgkmcnt(6)
	v_pk_mul_f32 v[26:27], v[0:1], v[8:9]
	v_pk_mul_f32 v[30:31], v[16:17], v[24:25] op_sel_hi:[1,0]
	v_pk_mul_f32 v[32:33], v[18:19], v[24:25] op_sel_hi:[1,0]
	v_pk_fma_f32 v[26:27], v[2:3], v[10:11], v[26:27]
	v_pk_mul_f32 v[38:39], v[0:1], v[120:121]
	v_pk_fma_f32 v[34:35], v[0:1], v[4:5], v[30:31]
	v_add_f32_e32 v28, v26, v27
	v_pk_fma_f32 v[36:37], v[2:3], v[6:7], v[32:33]
	v_pk_fma_f32 v[38:39], v[2:3], v[122:123], v[38:39]
	v_add_f32_dpp v28, v28, v28 row_ror:8 row_mask:0xf bank_mask:0xf bound_ctrl:1
	ds_read_b128 v[108:111], v40 offset:41728
	ds_read_b128 v[116:119], v40 offset:42240
	v_add_f32_dpp v28, v28, v28 row_ror:4 row_mask:0xf bank_mask:0xf bound_ctrl:1
	v_add_f32_e32 v54, v38, v39
	ds_read_b128 v[104:107], v40 offset:41472
	v_add_f32_dpp v28, v28, v28 row_ror:2 row_mask:0xf bank_mask:0xf bound_ctrl:1
	ds_read_b128 v[120:123], v40 offset:42496
	ds_read_b128 v[112:115], v40 offset:41984
	v_add_f32_dpp v28, v28, v28 row_ror:1 row_mask:0xf bank_mask:0xf bound_ctrl:1
	v_add_f32_dpp v144, v192, v192 row_half_mirror row_mask:0xf bank_mask:0xa
	v_cndmask_b32_e64 v155, v141, v143, s[8:9]
	v_pk_fma_f32 v[0:1], v[12:13], v[28:29], v[34:35] op_sel_hi:[1,0,1]
	v_pk_fma_f32 v[2:3], v[14:15], v[28:29], v[36:37] op_sel_hi:[1,0,1]
	v_add_f32_dpp v145, v155, v145 quad_perm:[2,3,0,1] row_mask:0xf bank_mask:0xf bound_ctrl:1
	v_cndmask_b32_e64 v146, v144, v142, s[8:9]
	v_pk_mul_f32 v[26:27], v[0:1], v[64:65]
	v_pk_mul_f32 v[30:31], v[72:73], v[24:25] op_sel:[0,1] op_sel_hi:[1,1]
	v_pk_mul_f32 v[32:33], v[74:75], v[24:25] op_sel:[0,1] op_sel_hi:[1,1]
	v_pk_fma_f32 v[26:27], v[2:3], v[66:67], v[26:27]
	v_pk_mul_f32 v[38:39], v[0:1], v[20:21]
	v_pk_fma_f32 v[34:35], v[0:1], v[60:61], v[30:31]
	v_add_f32_e32 v28, v26, v27
	v_pk_fma_f32 v[36:37], v[2:3], v[62:63], v[32:33]
	v_pk_fma_f32 v[38:39], v[2:3], v[22:23], v[38:39]
	v_add_f32_dpp v28, v28, v28 row_ror:8 row_mask:0xf bank_mask:0xf bound_ctrl:1
	ds_read_b128 v[8:11], v40 offset:43264
	ds_read_b128 v[16:19], v40 offset:43776
	v_add_f32_dpp v28, v28, v28 row_ror:4 row_mask:0xf bank_mask:0xf bound_ctrl:1
	v_add_f32_e32 v55, v38, v39
	ds_read2st64_b32 v[24:25], v52 offset0:173 offset1:179
	v_add_f32_dpp v28, v28, v28 row_ror:2 row_mask:0xf bank_mask:0xf bound_ctrl:1
	ds_read_b128 v[4:7], v40 offset:43008
	ds_read_b128 v[20:23], v40 offset:44032
	v_add_f32_dpp v28, v28, v28 row_ror:1 row_mask:0xf bank_mask:0xf bound_ctrl:1
	ds_read_b128 v[12:15], v40 offset:43520
	v_cndmask_b32_e64 v157, v142, v144, s[8:9]
	v_pk_fma_f32 v[0:1], v[68:69], v[28:29], v[34:35] op_sel_hi:[1,0,1]
	v_pk_fma_f32 v[2:3], v[70:71], v[28:29], v[36:37] op_sel_hi:[1,0,1]
	v_add_f32_dpp v146, v157, v146 quad_perm:[2,3,0,1] row_mask:0xf bank_mask:0xf bound_ctrl:1
	s_waitcnt lgkmcnt(6)
	v_pk_mul_f32 v[26:27], v[0:1], v[86:87]
	v_pk_mul_f32 v[30:31], v[94:95], v[102:103] op_sel_hi:[1,0]
	v_pk_mul_f32 v[32:33], v[96:97], v[102:103] op_sel_hi:[1,0]
	v_pk_fma_f32 v[26:27], v[2:3], v[88:89], v[26:27]
	v_pk_mul_f32 v[38:39], v[0:1], v[76:77]
	v_pk_fma_f32 v[34:35], v[0:1], v[82:83], v[30:31]
	v_add_f32_e32 v28, v26, v27
	v_pk_fma_f32 v[36:37], v[2:3], v[84:85], v[32:33]
	v_pk_fma_f32 v[38:39], v[2:3], v[78:79], v[38:39]
	v_add_f32_dpp v28, v28, v28 row_ror:8 row_mask:0xf bank_mask:0xf bound_ctrl:1
	ds_read_b128 v[64:67], v40 offset:44800
	ds_read_b128 v[72:75], v40 offset:45312
	v_add_f32_dpp v28, v28, v28 row_ror:4 row_mask:0xf bank_mask:0xf bound_ctrl:1
	v_add_f32_e32 v56, v38, v39
	ds_read_b128 v[60:63], v40 offset:44544
	v_add_f32_dpp v28, v28, v28 row_ror:2 row_mask:0xf bank_mask:0xf bound_ctrl:1
	ds_read_b128 v[76:79], v40 offset:45568
	ds_read_b128 v[68:71], v40 offset:45056
	v_add_f32_dpp v28, v28, v28 row_ror:1 row_mask:0xf bank_mask:0xf bound_ctrl:1
	v_cndmask_b32_e64 v147, v146, v145, s[10:11]
	v_cndmask_b32_e64 v159, v145, v146, s[10:11]
	v_pk_fma_f32 v[0:1], v[90:91], v[28:29], v[34:35] op_sel_hi:[1,0,1]
	v_pk_fma_f32 v[2:3], v[92:93], v[28:29], v[36:37] op_sel_hi:[1,0,1]
	v_add_f32_dpp v147, v159, v147 quad_perm:[1,0,3,2] row_mask:0xf bank_mask:0xf bound_ctrl:1
	v_pk_mul_f32 v[26:27], v[0:1], v[108:109]
	v_pk_mul_f32 v[30:31], v[116:117], v[102:103] op_sel:[0,1] op_sel_hi:[1,1]
	v_pk_mul_f32 v[32:33], v[118:119], v[102:103] op_sel:[0,1] op_sel_hi:[1,1]
	v_pk_fma_f32 v[26:27], v[2:3], v[110:111], v[26:27]
	v_pk_mul_f32 v[38:39], v[0:1], v[98:99]
	v_pk_fma_f32 v[34:35], v[0:1], v[104:105], v[30:31]
	v_add_f32_e32 v28, v26, v27
	v_pk_fma_f32 v[36:37], v[2:3], v[106:107], v[32:33]
	v_pk_fma_f32 v[38:39], v[2:3], v[100:101], v[38:39]
	v_add_f32_dpp v28, v28, v28 row_ror:8 row_mask:0xf bank_mask:0xf bound_ctrl:1
	ds_read_b128 v[86:89], v40 offset:46336
	ds_read_b128 v[94:97], v40 offset:46848
	v_add_f32_dpp v28, v28, v28 row_ror:4 row_mask:0xf bank_mask:0xf bound_ctrl:1
	v_add_f32_e32 v57, v38, v39
	ds_read2st64_b32 v[102:103], v52 offset0:185 offset1:191
	v_add_f32_dpp v28, v28, v28 row_ror:2 row_mask:0xf bank_mask:0xf bound_ctrl:1
	ds_read_b128 v[82:85], v40 offset:46080
	ds_read_b128 v[98:101], v40 offset:47104
	v_add_f32_dpp v28, v28, v28 row_ror:1 row_mask:0xf bank_mask:0xf bound_ctrl:1
	ds_read_b128 v[90:93], v40 offset:46592
	v_pk_fma_f32 v[0:1], v[112:113], v[28:29], v[34:35] op_sel_hi:[1,0,1]
	v_pk_fma_f32 v[2:3], v[114:115], v[28:29], v[36:37] op_sel_hi:[1,0,1]
	s_waitcnt lgkmcnt(6)
; __global__ void __launch_bounds__(512, 2) fwd_megakernel(Args a) {
;     ...
;                 for (int i = 0; i < NCH; ++i) { P3_CONS(i); __syncthreads(); }
	v_pk_mul_f32 v[26:27], v[0:1], v[8:9]
	v_pk_mul_f32 v[30:31], v[16:17], v[24:25] op_sel_hi:[1,0]
	v_pk_mul_f32 v[32:33], v[18:19], v[24:25] op_sel_hi:[1,0]
	v_pk_fma_f32 v[26:27], v[2:3], v[10:11], v[26:27]
	v_pk_mul_f32 v[38:39], v[0:1], v[120:121]
	v_pk_fma_f32 v[34:35], v[0:1], v[4:5], v[30:31]
	v_add_f32_e32 v28, v26, v27
	v_pk_fma_f32 v[36:37], v[2:3], v[6:7], v[32:33]
	v_pk_fma_f32 v[38:39], v[2:3], v[122:123], v[38:39]
	v_add_f32_dpp v28, v28, v28 row_ror:8 row_mask:0xf bank_mask:0xf bound_ctrl:1
	ds_read_b128 v[108:111], v40 offset:47872
	ds_read_b128 v[116:119], v40 offset:48384
	v_add_f32_dpp v28, v28, v28 row_ror:4 row_mask:0xf bank_mask:0xf bound_ctrl:1
	v_add_f32_e32 v58, v38, v39
	ds_read_b128 v[104:107], v40 offset:47616
	v_add_f32_dpp v28, v28, v28 row_ror:2 row_mask:0xf bank_mask:0xf bound_ctrl:1
	ds_read_b128 v[120:123], v40 offset:48640
	ds_read_b128 v[112:115], v40 offset:48128
	v_add_f32_dpp v28, v28, v28 row_ror:1 row_mask:0xf bank_mask:0xf bound_ctrl:1
	v_pk_fma_f32 v[0:1], v[12:13], v[28:29], v[34:35] op_sel_hi:[1,0,1]
	v_pk_fma_f32 v[2:3], v[14:15], v[28:29], v[36:37] op_sel_hi:[1,0,1]
	v_pk_mul_f32 v[26:27], v[0:1], v[64:65]
	v_pk_mul_f32 v[30:31], v[72:73], v[24:25] op_sel:[0,1] op_sel_hi:[1,1]
	v_pk_mul_f32 v[32:33], v[74:75], v[24:25] op_sel:[0,1] op_sel_hi:[1,1]
	v_pk_fma_f32 v[26:27], v[2:3], v[66:67], v[26:27]
	v_pk_mul_f32 v[38:39], v[0:1], v[20:21]
	v_pk_fma_f32 v[34:35], v[0:1], v[60:61], v[30:31]
	v_add_f32_e32 v28, v26, v27
	v_pk_fma_f32 v[36:37], v[2:3], v[62:63], v[32:33]
	v_pk_fma_f32 v[38:39], v[2:3], v[22:23], v[38:39]
	v_add_f32_dpp v28, v28, v28 row_ror:8 row_mask:0xf bank_mask:0xf bound_ctrl:1
	s_nop 1
	v_add_f32_dpp v28, v28, v28 row_ror:4 row_mask:0xf bank_mask:0xf bound_ctrl:1
	v_add_f32_e32 v59, v38, v39
	s_nop 0
	v_add_f32_dpp v28, v28, v28 row_ror:2 row_mask:0xf bank_mask:0xf bound_ctrl:1
	s_nop 1
	v_add_f32_dpp v28, v28, v28 row_ror:1 row_mask:0xf bank_mask:0xf bound_ctrl:1
	v_pk_fma_f32 v[0:1], v[68:69], v[28:29], v[34:35] op_sel_hi:[1,0,1]
	v_pk_fma_f32 v[2:3], v[70:71], v[28:29], v[36:37] op_sel_hi:[1,0,1]
	s_waitcnt lgkmcnt(0)
	v_pk_mul_f32 v[26:27], v[0:1], v[86:87]
	v_pk_mul_f32 v[30:31], v[94:95], v[102:103] op_sel_hi:[1,0]
	v_pk_mul_f32 v[32:33], v[96:97], v[102:103] op_sel_hi:[1,0]
	v_pk_fma_f32 v[26:27], v[2:3], v[88:89], v[26:27]
	v_pk_mul_f32 v[38:39], v[0:1], v[76:77]
	v_pk_fma_f32 v[34:35], v[0:1], v[82:83], v[30:31]
	v_add_f32_e32 v28, v26, v27
	v_pk_fma_f32 v[36:37], v[2:3], v[84:85], v[32:33]
	v_pk_fma_f32 v[38:39], v[2:3], v[78:79], v[38:39]
	v_add_f32_dpp v28, v28, v28 row_ror:8 row_mask:0xf bank_mask:0xf bound_ctrl:1
	s_nop 1
	v_add_f32_dpp v28, v28, v28 row_ror:4 row_mask:0xf bank_mask:0xf bound_ctrl:1
	v_add_f32_e32 v126, v38, v39
	s_nop 0
	v_add_f32_dpp v28, v28, v28 row_ror:2 row_mask:0xf bank_mask:0xf bound_ctrl:1
	s_nop 1
	v_add_f32_dpp v28, v28, v28 row_ror:1 row_mask:0xf bank_mask:0xf bound_ctrl:1
	v_pk_fma_f32 v[0:1], v[90:91], v[28:29], v[34:35] op_sel_hi:[1,0,1]
	v_pk_fma_f32 v[2:3], v[92:93], v[28:29], v[36:37] op_sel_hi:[1,0,1]
	v_pk_mul_f32 v[26:27], v[0:1], v[108:109]
	v_pk_mul_f32 v[30:31], v[116:117], v[102:103] op_sel:[0,1] op_sel_hi:[1,1]
	v_pk_mul_f32 v[32:33], v[118:119], v[102:103] op_sel:[0,1] op_sel_hi:[1,1]
	v_pk_fma_f32 v[26:27], v[2:3], v[110:111], v[26:27]
	v_pk_mul_f32 v[38:39], v[0:1], v[98:99]
	v_pk_fma_f32 v[34:35], v[0:1], v[104:105], v[30:31]
	v_add_f32_e32 v28, v26, v27
	v_pk_fma_f32 v[36:37], v[2:3], v[106:107], v[32:33]
	v_pk_fma_f32 v[38:39], v[2:3], v[100:101], v[38:39]
	v_add_f32_dpp v28, v28, v28 row_ror:8 row_mask:0xf bank_mask:0xf bound_ctrl:1
	s_nop 1
	v_add_f32_dpp v28, v28, v28 row_ror:4 row_mask:0xf bank_mask:0xf bound_ctrl:1
	v_add_f32_e32 v127, v38, v39
	s_nop 0
	v_add_f32_dpp v28, v28, v28 row_ror:2 row_mask:0xf bank_mask:0xf bound_ctrl:1
	s_nop 1
	v_add_f32_dpp v28, v28, v28 row_ror:1 row_mask:0xf bank_mask:0xf bound_ctrl:1
	v_pk_fma_f32 v[0:1], v[112:113], v[28:29], v[34:35] op_sel_hi:[1,0,1]
	v_pk_fma_f32 v[2:3], v[114:115], v[28:29], v[36:37] op_sel_hi:[1,0,1]
	s_mov_b32 s2, 0xffff0000
	s_mov_b32 s3, -1
	v_lshl_add_u64 v[148:149], v[44:45], 0, s[2:3]
	global_store_dword v[148:149], v147, off
	v_pk_mul_f32 v[38:39], v[0:1], v[120:121]
	s_mov_b64 s[2:3], 0x20000
	v_lshl_add_u64 v[44:45], v[44:45], 0, s[2:3]
	s_add_i32 s14, s14, 1
	v_pk_fma_f32 v[38:39], v[2:3], v[122:123], v[38:39]
	s_cmpk_lg_i32 s14, 0x80
	s_waitcnt lgkmcnt(0)
	s_nop 0
	v_add_f32_e32 v139, v38, v39
	s_barrier
	s_cbranch_scc1 .LBB0_308
	v_add_f32_dpp v185, v46, v46 row_mirror row_mask:0xf bank_mask:0x3
	v_add_f32_dpp v186, v47, v47 row_mirror row_mask:0xf bank_mask:0x3
	v_add_f32_dpp v187, v48, v48 row_mirror row_mask:0xf bank_mask:0x3
	v_add_f32_dpp v185, v55, v55 row_mirror row_mask:0xf bank_mask:0xc
	v_add_f32_dpp v186, v56, v56 row_mirror row_mask:0xf bank_mask:0xc
	v_add_f32_dpp v187, v57, v57 row_mirror row_mask:0xf bank_mask:0xc
	v_add_f32_dpp v188, v49, v49 row_mirror row_mask:0xf bank_mask:0x3
	v_add_f32_dpp v189, v50, v50 row_mirror row_mask:0xf bank_mask:0x3
	v_add_f32_dpp v190, v51, v51 row_mirror row_mask:0xf bank_mask:0x3
	v_add_f32_dpp v188, v58, v58 row_mirror row_mask:0xf bank_mask:0xc
	v_add_f32_dpp v189, v59, v59 row_mirror row_mask:0xf bank_mask:0xc
	v_add_f32_dpp v190, v126, v126 row_mirror row_mask:0xf bank_mask:0xc
	v_add_f32_dpp v191, v53, v53 row_mirror row_mask:0xf bank_mask:0x3
	v_add_f32_dpp v192, v54, v54 row_mirror row_mask:0xf bank_mask:0x3
	v_add_f32_dpp v141, v185, v185 row_half_mirror row_mask:0xf bank_mask:0x5
	v_add_f32_dpp v191, v127, v127 row_mirror row_mask:0xf bank_mask:0xc
	v_add_f32_dpp v192, v139, v139 row_mirror row_mask:0xf bank_mask:0xc
	v_add_f32_dpp v141, v189, v189 row_half_mirror row_mask:0xf bank_mask:0xa
	v_add_f32_dpp v142, v186, v186 row_half_mirror row_mask:0xf bank_mask:0x5
	v_add_f32_dpp v143, v187, v187 row_half_mirror row_mask:0xf bank_mask:0x5
	v_add_f32_dpp v144, v188, v188 row_half_mirror row_mask:0xf bank_mask:0x5
	v_add_f32_dpp v142, v190, v190 row_half_mirror row_mask:0xf bank_mask:0xa
	v_add_f32_dpp v143, v191, v191 row_half_mirror row_mask:0xf bank_mask:0xa
	v_add_f32_dpp v144, v192, v192 row_half_mirror row_mask:0xf bank_mask:0xa
	s_nop 0
	v_cndmask_b32_e64 v145, v143, v141, s[8:9]
	v_cndmask_b32_e64 v155, v141, v143, s[8:9]
	v_cndmask_b32_e64 v146, v144, v142, s[8:9]
	v_cndmask_b32_e64 v157, v142, v144, s[8:9]
	v_add_f32_dpp v145, v155, v145 quad_perm:[2,3,0,1] row_mask:0xf bank_mask:0xf bound_ctrl:1
	s_nop 0
	v_add_f32_dpp v146, v157, v146 quad_perm:[2,3,0,1] row_mask:0xf bank_mask:0xf bound_ctrl:1
	s_nop 0
	s_nop 0
	v_cndmask_b32_e64 v147, v146, v145, s[10:11]
	v_cndmask_b32_e64 v159, v145, v146, s[10:11]
	s_nop 0
	s_nop 0
	v_add_f32_dpp v147, v159, v147 quad_perm:[1,0,3,2] row_mask:0xf bank_mask:0xf bound_ctrl:1
	s_mov_b32 s2, 0xfffe0000
	s_mov_b32 s3, -1
	v_lshl_add_u64 v[148:149], v[44:45], 0, s[2:3]
	global_store_dword v[148:149], v147, off
	s_mov_b64 s[14:15], 0

; #define LAS __attribute__((address_space(3)))
; DI unsigned f2h(float f) { return (unsigned)__builtin_bit_cast(u16, (_Float16)f); }
; __global__ void __launch_bounds__(512, 2) fwd_megakernel(Args a) {
;     ...
;                     const int key = tid >> 3, dc = tid & 7;
;                     const u32x4 kv = kvn, vv = vvn;
;                     if (kt > 0) { const size_t go = (size_t)(b * SEQ + k0 - 64 + key) * 1024 + h * 64 + dc * 8; kvn = *(const u32x4*)(Kg + go); vvn = *(const u32x4*)(Vg + go); }
;                     *(LAS u32x4*)(Ks + key * 72 + dc * 8) = kv;
;                     LAS u16* vp = Vt + (dc * 8) * 72 + key;
;                     vp[0 * 72] = (u16)(vv.x & 0xffffu); vp[1 * 72] = (u16)(vv.x >> 16); vp[2 * 72] = (u16)(vv.y & 0xffffu); vp[3 * 72] = (u16)(vv.y >> 16);
;                     vp[4 * 72] = (u16)(vv.z & 0xffffu); vp[5 * 72] = (u16)(vv.z >> 16); vp[6 * 72] = (u16)(vv.w & 0xffffu); vp[7 * 72] = (u16)(vv.w >> 16);
;                 }
;                 __syncthreads();
;                 if (!wdone && k0 < qw + 15) {
;                     f32x4 z[4];
; #pragma unroll
;                     for (int nt = 0; nt < 4; ++nt) { f32x4 c = (f32x4){0.f, 0.f, 0.f, 0.f};
; #pragma unroll
;                         for (int ks = 0; ks < 2; ++ks) { const f16x8 bk = *(const LAS f16x8*)(Ks + (16 * nt + lq) * 72 + 32 * ks + 8 * lg);
;                             c = __builtin_amdgcn_mfma_f32_16x16x32_f16(Aq[ks], bk, c, 0, 0, 0); }
;                         z[nt] = c; }
;                     bool msk[4][4];
; #pragma unroll
;                     for (int nt = 0; nt < 4; ++nt)
; #pragma unroll
;                         for (int j = 0; j < 4; ++j) { const float zz = z[nt][j];
;                             msk[nt][j] = (k0 + 16 * nt + lq) < (qw + 4 * lg + j);
;                             const float sp = fmaxf(zz, 0.f) + __logf(1.f + __expf(-fabsf(zz)));
;                             const float lk = msk[nt][j] ? -sp : 0.f;
;                             Ls[(4 * lg + j) * 72 + 16 * nt + lq] = (u16)f2h(lk); }
.LBB0_416:
	s_xor_b64 s[4:5], s[4:5], -1
	s_andn2_b64 vcc, exec, s[4:5]
	s_mov_b64 s[4:5], -1
	ds_write_b128 v89, v[60:63]
	ds_write_b16 v95, v56 offset:9216
	ds_write_b16_d16_hi v95, v56 offset:9360
	ds_write_b16 v95, v57 offset:9504
	ds_write_b16_d16_hi v95, v57 offset:9648
	ds_write_b16 v95, v58 offset:9792
	ds_write_b16_d16_hi v95, v58 offset:9936
	ds_write_b16 v95, v59 offset:10080
	ds_write_b16_d16_hi v95, v59 offset:10224
	s_waitcnt lgkmcnt(0)
	s_barrier
	s_cbranch_vccnz .LBB0_451
	s_add_i32 s4, s74, 64
	s_cmp_ge_u32 s4, s96
	s_mov_b64 s[4:5], 0
	s_cbranch_scc1 .LBB0_451
	ds_read_b128 v[56:59], v98
	ds_read_b128 v[60:63], v98 offset:64
	v_add_u32_e32 v2, s74, v162
	s_mov_b32 s54, s52
	s_mov_b32 s55, s52
	s_waitcnt lgkmcnt(1)
	v_mfma_f32_16x16x32_f16 v[56:59], v[40:43], v[56:59], 0
	s_mov_b32 s53, s52
	v_mov_b32_e32 v105, 0
	s_waitcnt lgkmcnt(0)
	v_mfma_f32_16x16x32_f16 v[68:71], v[44:47], v[60:63], v[56:59]
	s_nop 3
	ds_read_b128 v[56:59], v98 offset:2304
	ds_read_b128 v[60:63], v98 offset:2368
	ds_read_b128 v[72:75], v98 offset:4608
	ds_read_b128 v[76:79], v98 offset:4672
	v_mul_f32_e64 v1, |v68|, s97
	v_exp_f32_e32 v1, v1
	s_waitcnt lgkmcnt(3)
	v_mfma_f32_16x16x32_f16 v[56:59], v[40:43], v[56:59], 0
	v_add_f32_e32 v1, 1.0, v1
	s_nop 0
	s_waitcnt lgkmcnt(2)
	v_mfma_f32_16x16x32_f16 v[64:67], v[44:47], v[60:63], v[56:59]
	s_nop 3
	ds_read_b128 v[56:59], v98 offset:6912
	ds_read_b128 v[80:83], v98 offset:6976
	v_log_f32_e32 v1, v1
	s_waitcnt lgkmcnt(3)
	v_mfma_f32_16x16x32_f16 v[60:63], v[40:43], v[72:75], 0
	s_nop 0
	v_max_f32_e32 v3, 0, v68
	v_mul_f32_e32 v72, 0x3f317217, v1
	v_fma_f32 v72, v1, s94, -v72
	v_fmac_f32_e32 v72, 0x3377d1cf, v1
	v_fmac_f32_e32 v72, 0x3f317217, v1
	s_nop 0
	v_mul_f32_e64 v74, |v70|, s97
	v_exp_f32_e32 v74, v74
	v_mov_b32_e32 v1, v72
	s_nop 0
	s_nop 0
	v_add_f32_e32 v1, v3, v1
	v_mul_f32_e64 v3, |v69|, s97
	v_exp_f32_e32 v3, v3
	v_cvt_f16_f32_e64 v1, -v1
	v_add_u32_e32 v72, 64, v2
	v_cmp_lt_u32_e32 vcc, v72, v93
	v_add_f32_e32 v3, 1.0, v3
	s_nop 0
	v_cndmask_b32_e32 v1, 0, v1, vcc
	ds_write_b16 v100, v1 offset:18432
	v_log_f32_e32 v3, v3
	s_nop 0
	v_max_f32_e32 v1, 0, v69
	s_waitcnt lgkmcnt(3)
	v_mfma_f32_16x16x32_f16 v[60:63], v[44:47], v[76:79], v[60:63]
	v_mul_f32_e32 v73, 0x3f317217, v3
	v_fma_f32 v73, v3, s94, -v73
	v_fmac_f32_e32 v73, 0x3377d1cf, v3
	v_fmac_f32_e32 v73, 0x3f317217, v3
	s_nop 0
	s_waitcnt lgkmcnt(2)
	v_mfma_f32_16x16x32_f16 v[56:59], v[40:43], v[56:59], 0
	v_mov_b32_e32 v3, v73
	s_nop 0
	s_nop 0
	v_add_f32_e32 v1, v1, v3
	v_add_f32_e32 v3, 1.0, v74
	s_nop 0
	v_cvt_f16_f32_e64 v1, -v1
	v_cmp_le_u32_e64 s[4:5], v72, v93
	s_nop 0
	s_nop 0
	v_log_f32_e32 v3, v3
	s_nop 0
	v_max_f32_e32 v73, 0, v70
	v_cndmask_b32_e64 v1, 0, v1, s[4:5]
	v_mul_f32_e32 v74, 0x3f317217, v3
	v_fma_f32 v74, v3, s94, -v74
	v_fmac_f32_e32 v74, 0x3377d1cf, v3
	v_fmac_f32_e32 v74, 0x3f317217, v3
	ds_write_b16 v100, v1 offset:18576
	s_waitcnt lgkmcnt(2)
	v_mfma_f32_16x16x32_f16 v[56:59], v[44:47], v[80:83], v[56:59]
	v_mov_b32_e32 v3, v74
	s_nop 0
	s_nop 0
	v_add_f32_e32 v3, v73, v3
	v_mul_f32_e64 v73, |v71|, s97
	v_cvt_f16_f32_e64 v3, -v3
	v_exp_f32_e32 v73, v73
	v_cmp_lt_u32_e64 s[6:7], v72, v103
	v_mul_f32_e64 v74, |v65|, s97
	v_exp_f32_e32 v74, v74
	v_cndmask_b32_e64 v1, 0, v3, s[6:7]
	v_add_f32_e32 v3, 1.0, v73
	s_nop 0
	ds_write_b16 v100, v1 offset:18720
	s_nop 0
	v_log_f32_e32 v3, v3
	v_max_f32_e32 v1, 0, v71
	v_mov_b64_e32 v[82:83], s[54:55]
	v_mov_b64_e32 v[80:81], s[52:53]
	v_mul_f32_e32 v73, 0x3f317217, v3
	v_fma_f32 v73, v3, s94, -v73
	v_fmac_f32_e32 v73, 0x3377d1cf, v3
	v_fmac_f32_e32 v73, 0x3f317217, v3
	s_nop 0
	s_nop 1
	v_mov_b32_e32 v3, v73
	s_nop 0
	s_nop 0
	v_add_f32_e32 v1, v1, v3
	v_cvt_f16_f32_e64 v1, -v1
	v_mul_f32_e64 v3, |v64|, s97
	v_exp_f32_e32 v3, v3
	v_cmp_lt_u32_e64 s[8:9], v72, v104
	s_nop 0
	v_max_f32_e32 v72, 0, v64
	v_cndmask_b32_e64 v1, 0, v1, s[8:9]
	ds_write_b16 v100, v1 offset:18864
	v_add_f32_e32 v1, 1.0, v3
	s_nop 1
	s_nop 0
	v_log_f32_e32 v1, v1
	v_add_u32_e32 v3, 0x50, v2
	v_mul_f32_e32 v73, 0x3f317217, v1
	v_fma_f32 v73, v1, s94, -v73
	v_fmac_f32_e32 v73, 0x3377d1cf, v1
	v_fmac_f32_e32 v73, 0x3f317217, v1
	s_nop 0
	s_nop 1
	v_mov_b32_e32 v1, v73
	s_nop 0
	s_nop 0
	v_add_f32_e32 v1, v72, v1
	v_add_f32_e32 v72, 1.0, v74
	s_nop 0
	v_cvt_f16_f32_e64 v1, -v1
	v_cmp_lt_u32_e64 s[10:11], v3, v93
	s_nop 0
	s_nop 0
	v_log_f32_e32 v72, v72
	s_nop 0
	v_max_f32_e32 v73, 0, v65
	v_cndmask_b32_e64 v1, 0, v1, s[10:11]
	v_mul_f32_e32 v74, 0x3f317217, v72
	v_fma_f32 v74, v72, s94, -v74
	v_fmac_f32_e32 v74, 0x3377d1cf, v72
	v_fmac_f32_e32 v74, 0x3f317217, v72
	s_nop 0
	ds_write_b16 v100, v1 offset:18464
	s_nop 0
	v_mov_b32_e32 v72, v74
	s_nop 0
	s_nop 0
	v_add_f32_e32 v72, v73, v72
	v_mul_f32_e64 v73, |v66|, s97
	v_cvt_f16_f32_e64 v72, -v72
	v_exp_f32_e32 v73, v73
	v_cmp_le_u32_e64 s[12:13], v3, v93
	v_mul_f32_e64 v74, |v67|, s97
	v_exp_f32_e32 v74, v74
	v_cndmask_b32_e64 v1, 0, v72, s[12:13]
	v_add_f32_e32 v72, 1.0, v73
	s_nop 0
	ds_write_b16 v100, v1 offset:18608
	s_nop 0
	v_log_f32_e32 v72, v72
	v_max_f32_e32 v1, 0, v66
	v_mul_f32_e32 v73, 0x3f317217, v72
	v_fma_f32 v73, v72, s94, -v73
	v_fmac_f32_e32 v73, 0x3377d1cf, v72
	v_fmac_f32_e32 v73, 0x3f317217, v72
	s_nop 0
	s_nop 1
	v_mov_b32_e32 v72, v73
	s_nop 0
	s_nop 0
	v_add_f32_e32 v1, v1, v72
	v_add_f32_e32 v72, 1.0, v74
	s_nop 0
	v_cvt_f16_f32_e64 v1, -v1
	v_cmp_lt_u32_e64 s[16:17], v3, v103
	s_nop 0
	s_nop 0
	v_log_f32_e32 v72, v72
	s_nop 0
	v_max_f32_e32 v73, 0, v67
	v_cndmask_b32_e64 v1, 0, v1, s[16:17]
	v_mul_f32_e32 v74, 0x3f317217, v72
	v_fma_f32 v74, v72, s94, -v74
; #define LAS __attribute__((address_space(3)))
; DI unsigned f2h(float f) { return (unsigned)__builtin_bit_cast(u16, (_Float16)f); }
; #define LDS_WAIT() asm volatile("s_waitcnt lgkmcnt(0)" ::: "memory")
; __global__ void __launch_bounds__(512, 2) fwd_megakernel(Args a) {
;     ...
;                         for (int j = 0; j < 4; ++j) { const float zz = z[nt][j];
;                             msk[nt][j] = (k0 + 16 * nt + lq) < (qw + 4 * lg + j);
;                             const float sp = fmaxf(zz, 0.f) + __logf(1.f + __expf(-fabsf(zz)));
;                             const float lk = msk[nt][j] ? -sp : 0.f;
;                             Ls[(4 * lg + j) * 72 + 16 * nt + lq] = (u16)f2h(lk); }
;                     LDS_WAIT();
;                     f16x8 Al[2];
; #pragma unroll
;                     for (int ks = 0; ks < 2; ++ks) Al[ks] = *(const LAS f16x8*)(Ls + lq * 72 + 32 * ks + 8 * lg);
;                     LDS_WAIT();
;                     f32x4 cs[4];
; #pragma unroll
;                     for (int nt = 0; nt < 4; ++nt) { f32x4 c = (f32x4){0.f, 0.f, 0.f, 0.f};
; #pragma unroll
;                         for (int ks = 0; ks < 2; ++ks) c = __builtin_amdgcn_mfma_f32_16x16x32_f16(Al[ks], Tb[ks][nt], c, 0, 0, 0);
;                         cs[nt] = c; }
;                     float tot[4];
; #pragma unroll
;                     for (int j = 0; j < 4; ++j) tot[j] = __shfl(cs[0][j], lane & 48);
; #pragma unroll
;                     for (int nt = 0; nt < 4; ++nt)
; #pragma unroll
;                         for (int j = 0; j < 4; ++j) { const float p = msk[nt][j] ? __expf(z[nt][j] + cs[nt][j] + carry[j]) : 0.f;
;                             Ls[(4 * lg + j) * 72 + 16 * nt + lq] = (u16)f2h(p); }
; #pragma unroll
;                     for (int j = 0; j < 4; ++j) carry[j] += tot[j];
;                     LDS_WAIT();
;                     f16x8 Ap[2];
; #pragma unroll
;                     for (int ks = 0; ks < 2; ++ks) Ap[ks] = *(const LAS f16x8*)(Ls + lq * 72 + 32 * ks + 8 * lg);
; #pragma unroll
;                     for (int nd = 0; nd < 4; ++nd)
; #pragma unroll
;                         for (int ks = 0; ks < 2; ++ks) { const f16x8 bv = *(const LAS f16x8*)(Vt + (16 * nd + lq) * 72 + 32 * ks + 8 * lg);
;                             O[nd] = __builtin_amdgcn_mfma_f32_16x16x32_f16(Ap[ks], bv, O[nd], 0, 0, 0); }
	v_fmac_f32_e32 v74, 0x3377d1cf, v72
	v_fmac_f32_e32 v74, 0x3f317217, v72
	s_nop 0
	ds_write_b16 v100, v1 offset:18752
	s_nop 0
	v_mov_b32_e32 v72, v74
	s_nop 0
	s_nop 0
	v_add_f32_e32 v72, v73, v72
	v_mul_f32_e64 v73, |v60|, s97
	v_exp_f32_e32 v73, v73
	v_cvt_f16_f32_e64 v72, -v72
	v_cmp_lt_u32_e64 s[18:19], v3, v104
	v_mul_f32_e64 v74, |v62|, s97
	v_add_f32_e32 v3, 1.0, v73
	s_nop 0
	v_cndmask_b32_e64 v1, 0, v72, s[18:19]
	ds_write_b16 v100, v1 offset:18896
	v_log_f32_e32 v3, v3
	s_nop 0
	v_max_f32_e32 v1, 0, v60
	v_exp_f32_e32 v74, v74
	v_mul_f32_e32 v72, 0x3f317217, v3
	v_fma_f32 v72, v3, s94, -v72
	v_fmac_f32_e32 v72, 0x3377d1cf, v3
	v_fmac_f32_e32 v72, 0x3f317217, v3
	s_nop 0
	s_nop 1
	v_mov_b32_e32 v3, v72
	s_nop 0
	s_nop 0
	v_add_f32_e32 v1, v1, v3
	v_mul_f32_e64 v3, |v61|, s97
	v_exp_f32_e32 v3, v3
	v_cvt_f16_f32_e64 v1, -v1
	v_add_u32_e32 v72, 0x60, v2
	v_cmp_lt_u32_e64 s[20:21], v72, v93
	v_add_f32_e32 v3, 1.0, v3
	s_nop 0
	v_cndmask_b32_e64 v1, 0, v1, s[20:21]
	ds_write_b16 v100, v1 offset:18496
	v_log_f32_e32 v3, v3
	s_nop 0
	v_max_f32_e32 v1, 0, v61
	v_add_u32_e32 v2, 0x70, v2
	v_mul_f32_e32 v73, 0x3f317217, v3
	v_fma_f32 v73, v3, s94, -v73
	v_fmac_f32_e32 v73, 0x3377d1cf, v3
	v_fmac_f32_e32 v73, 0x3f317217, v3
	s_nop 0
	s_nop 1
	v_mov_b32_e32 v3, v73
	s_nop 0
	s_nop 0
	v_add_f32_e32 v1, v1, v3
	v_add_f32_e32 v3, 1.0, v74
	s_nop 0
	v_cvt_f16_f32_e64 v1, -v1
	v_cmp_le_u32_e64 s[22:23], v72, v93
	s_nop 0
	s_nop 0
	v_log_f32_e32 v3, v3
	s_nop 0
	v_max_f32_e32 v73, 0, v62
	v_cndmask_b32_e64 v1, 0, v1, s[22:23]
	v_mul_f32_e32 v74, 0x3f317217, v3
	v_fma_f32 v74, v3, s94, -v74
	v_fmac_f32_e32 v74, 0x3377d1cf, v3
	v_fmac_f32_e32 v74, 0x3f317217, v3
	s_nop 0
	ds_write_b16 v100, v1 offset:18640
	s_nop 0
	v_mov_b32_e32 v3, v74
	s_nop 0
	s_nop 0
	v_add_f32_e32 v3, v73, v3
	v_mul_f32_e64 v73, |v63|, s97
	v_cvt_f16_f32_e64 v3, -v3
	v_exp_f32_e32 v73, v73
	v_cmp_lt_u32_e64 s[24:25], v72, v103
	s_nop 1
	v_cndmask_b32_e64 v1, 0, v3, s[24:25]
	v_add_f32_e32 v3, 1.0, v73
	s_nop 0
	ds_write_b16 v100, v1 offset:18784
	s_nop 0
	v_log_f32_e32 v3, v3
	v_max_f32_e32 v1, 0, v63
	v_mul_f32_e32 v73, 0x3f317217, v3
	v_fma_f32 v73, v3, s94, -v73
	v_fmac_f32_e32 v73, 0x3377d1cf, v3
	v_fmac_f32_e32 v73, 0x3f317217, v3
	s_nop 0
	s_nop 1
	v_mov_b32_e32 v3, v73
	s_nop 0
	s_nop 0
	v_add_f32_e32 v1, v1, v3
	v_cvt_f16_f32_e64 v1, -v1
	v_mul_f32_e64 v3, |v56|, s97
	v_exp_f32_e32 v3, v3
	v_cmp_lt_u32_e64 s[26:27], v72, v104
	v_mul_f32_e64 v73, |v57|, s97
	v_exp_f32_e32 v73, v73
	v_cndmask_b32_e64 v1, 0, v1, s[26:27]
	ds_write_b16 v100, v1 offset:18928
	v_add_f32_e32 v1, 1.0, v3
	s_nop 1
	s_nop 0
	v_log_f32_e32 v1, v1
	s_nop 0
	v_max_f32_e32 v3, 0, v56
	v_mul_f32_e32 v72, 0x3f317217, v1
	v_fma_f32 v72, v1, s94, -v72
	v_fmac_f32_e32 v72, 0x3377d1cf, v1
	v_fmac_f32_e32 v72, 0x3f317217, v1
	s_nop 0
	s_nop 1
	v_mov_b32_e32 v1, v72
	s_nop 0
	s_nop 0
	v_add_f32_e32 v1, v3, v1
	v_add_f32_e32 v3, 1.0, v73
	s_nop 0
	v_cvt_f16_f32_e64 v1, -v1
	v_cmp_lt_u32_e64 s[28:29], v2, v93
	s_nop 0
	s_nop 0
	v_log_f32_e32 v3, v3
	s_nop 0
	v_max_f32_e32 v72, 0, v57
	v_cndmask_b32_e64 v1, 0, v1, s[28:29]
	v_mul_f32_e32 v73, 0x3f317217, v3
	v_fma_f32 v73, v3, s94, -v73
	v_fmac_f32_e32 v73, 0x3377d1cf, v3
	v_fmac_f32_e32 v73, 0x3f317217, v3
	s_nop 0
	ds_write_b16 v100, v1 offset:18528
	s_nop 0
	v_mov_b32_e32 v3, v73
	s_nop 0
	s_nop 0
	v_add_f32_e32 v3, v72, v3
	v_mul_f32_e64 v72, |v58|, s97
	v_cvt_f16_f32_e64 v3, -v3
	v_exp_f32_e32 v72, v72
	v_cmp_le_u32_e64 s[30:31], v2, v93
	s_nop 1
	v_cndmask_b32_e64 v1, 0, v3, s[30:31]
	v_add_f32_e32 v3, 1.0, v72
	s_nop 0
	ds_write_b16 v100, v1 offset:18672
	s_nop 0
	v_log_f32_e32 v3, v3
	s_nop 0
	v_max_f32_e32 v1, 0, v58
	v_mul_f32_e32 v72, 0x3f317217, v3
	v_fma_f32 v72, v3, s94, -v72
	v_fmac_f32_e32 v72, 0x3377d1cf, v3
	v_fmac_f32_e32 v72, 0x3f317217, v3
	s_nop 0
	s_nop 1
	v_mov_b32_e32 v3, v72
	v_mul_f32_e64 v72, |v59|, s97
	v_exp_f32_e32 v72, v72
	s_nop 0
	v_add_f32_e32 v1, v1, v3
	v_cvt_f16_f32_e64 v1, -v1
	v_add_f32_e32 v3, 1.0, v72
	s_nop 1
	s_nop 0
	v_log_f32_e32 v3, v3
	s_nop 0
	v_max_f32_e32 v72, 0, v59
	v_mul_f32_e32 v73, 0x3f317217, v3
	v_fma_f32 v73, v3, s94, -v73
	v_fmac_f32_e32 v73, 0x3377d1cf, v3
	v_fmac_f32_e32 v73, 0x3f317217, v3
	s_nop 0
	s_nop 1
	v_mov_b32_e32 v3, v73
	s_nop 0
	s_nop 0
	v_add_f32_e32 v3, v72, v3
	v_cvt_f16_f32_e64 v3, -v3
	v_cmp_lt_u32_e64 s[36:37], v2, v103
	v_cmp_lt_u32_e64 s[34:35], v2, v104
	v_mov_b32_e32 v2, v0
	v_cndmask_b32_e64 v1, 0, v1, s[36:37]
	ds_write_b16 v100, v1 offset:18816
	v_cndmask_b32_e64 v1, 0, v3, s[34:35]
	ds_write_b16 v100, v1 offset:18960
	s_waitcnt lgkmcnt(0)
	ds_read_b128 v[72:75], v101 offset:18432
	ds_read_b128 v[106:109], v101 offset:18496
	s_waitcnt lgkmcnt(1)
	v_mfma_f32_16x16x32_f16 v[76:79], v[72:75], v[4:7], 0
	v_mov_b32_e32 v1, v0
	v_mov_b32_e32 v3, v0
	s_waitcnt lgkmcnt(0)
	s_waitcnt lgkmcnt(0)
	v_mfma_f32_16x16x32_f16 v[84:87], v[106:109], v[80:83], v[76:79]
	v_mfma_f32_16x16x32_f16 v[76:79], v[72:75], v[8:11], 0
	v_mfma_f32_16x16x32_f16 v[72:75], v[72:75], v[0:3], 0
	s_nop 5
	ds_bpermute_b32 v2, v102, v84
	ds_bpermute_b32 v3, v102, v85
	ds_bpermute_b32 v96, v102, v86
	ds_bpermute_b32 v97, v102, v87
	v_mfma_f32_16x16x32_f16 v[80:83], v[106:109], v[80:83], v[76:79]
	v_mov_b32_e32 v1, 0
	v_mfma_f32_16x16x32_f16 v[76:79], v[106:109], v[12:15], v[72:75]
	v_mfma_f32_16x16x32_f16 v[72:75], v[106:109], v[16:19], v[72:75]
	s_and_saveexec_b64 s[14:15], vcc
	s_cbranch_execz .LBB0_420
	v_add_f32_e32 v68, v68, v84
	v_add_f32_e32 v68, v36, v68
	v_mul_f32_e32 v68, 0x3fb8aa3b, v68
	v_exp_f32_e32 v68, v68
	s_nop 0
	v_cvt_f16_f32_e32 v105, v68
